# P5 epilogue: 8 serialized ssq loads (vmcnt(0) each) hoisted into one batch with counted waits
# baseline (speedup 1.0000x reference)
; __device__ __forceinline__ unsigned cvt_pk_bf16(float lo, float hi) { const f32x2c_t v = {lo, hi}; const bf16x2c_t b = __builtin_convertvector(v, bf16x2c_t); return __builtin_bit_cast(unsigned, b); }
;     __device__ __forceinline__ void operator()(const f32x4 (&acc)[2][2][4][2], const Unit& u, int wr, int wc, int fr, int fq) const {
;     ...
;             for (int m = 0; m < 4; ++m) { const size_t r = (size_t)(row0 + ai * HALF + m * 16);
;                 const f32x4 pq = *(const f32x4*)(ssq + r * 16 + 4 * fq);
;                 float ss = (pq[0] + pq[1]) + (pq[2] + pq[3]); ss += __shfl_xor(ss, 16); ss += __shfl_xor(ss, 32);
;                 const float rs = __builtin_amdgcn_rsqf(ss * (1.f / DM) + RMS_EPS);
; #pragma unroll
;                 for (int bj = 0; bj < 2; ++bj) { f32x4 v0 = acc[ai][bj][m][0] * rs, v1 = acc[ai][bj][m][1] * rs;
; #pragma unroll
;                     for (int e = 0; e < 4; ++e) { const float a = fmaxf(v0[e], 0.f), b = fmaxf(v1[e], 0.f); v0[e] = a * a; v1[e] = b * b; }
;                     u32x4 w; w.x = cvt_pk_bf16(v0[0], v0[1]); w.y = cvt_pk_bf16(v0[2], v0[3]); w.z = cvt_pk_bf16(v1[0], v1[1]); w.w = cvt_pk_bf16(v1[2], v1[3]);
;                     *(u32x4*)(O + r * DFF + col0 + bj * HALF) = w; } }
.LBB0_394:
	v_lshl_add_u32 v148, s38, 8, v150
	v_ashrrev_i32_e32 v149, 31, v148
	v_lshlrev_b64 v[146:147], 6, v[148:149]
	v_lshl_add_u64 v[146:147], v[136:137], 0, v[146:147]
	s_mov_b64 s[0:1], 0x2000
	global_load_dwordx4 v[170:173], v[146:147], off
	global_load_dwordx4 v[174:177], v[146:147], off offset:1024
	global_load_dwordx4 v[178:181], v[146:147], off offset:2048
	global_load_dwordx4 v[182:185], v[146:147], off offset:3072
	v_lshl_add_u64 v[202:203], v[146:147], 0, s[0:1]
	global_load_dwordx4 v[186:189], v[202:203], off
	global_load_dwordx4 v[190:193], v[202:203], off offset:1024
	global_load_dwordx4 v[194:197], v[202:203], off offset:2048
	global_load_dwordx4 v[198:201], v[202:203], off offset:3072
	v_and_b32_e32 v147, 64, v156
	v_xor_b32_e32 v158, 16, v156
	v_add_u32_e32 v166, 64, v147
	v_cmp_lt_i32_e32 vcc, v158, v166
	v_xor_b32_e32 v159, 32, v156
	v_lshl_or_b32 v146, s56, 8, v152
	v_cndmask_b32_e32 v158, v156, v158, vcc
	v_lshlrev_b32_e32 v158, 2, v158
	v_cmp_lt_i32_e32 vcc, v159, v166
	v_ashrrev_i32_e32 v147, 31, v146
	v_lshlrev_b64 v[146:147], 1, v[146:147]
	v_cndmask_b32_e32 v159, v156, v159, vcc
	v_lshlrev_b32_e32 v159, 2, v159
	s_andn2_b64 vcc, exec, s[4:5]
	s_mov_b64 s[4:5], -1
	s_waitcnt vmcnt(7)
	s_nop 1
	v_add_f32_e32 v160, v170, v171
	v_add_f32_e32 v161, v172, v173
	s_nop 0
	v_add_f32_e32 v161, v160, v161
	ds_bpermute_b32 v162, v158, v161
	v_or_b32_e32 v160, 16, v148
	s_waitcnt lgkmcnt(0)
	v_add_f32_e32 v164, v161, v162
	ds_bpermute_b32 v165, v159, v164
	v_lshlrev_b64 v[162:163], 13, v[148:149]
	v_ashrrev_i32_e32 v161, 31, v160
	v_lshl_add_u64 v[162:163], s[28:29], 0, v[162:163]
	v_lshlrev_b64 v[166:167], 6, v[160:161]
	s_waitcnt lgkmcnt(0)
	v_add_f32_e32 v149, v164, v165
	v_fmamk_f32 v149, v149, 0x3a800000, v157
	v_rsq_f32_e32 v164, v149
	v_lshl_add_u64 v[162:163], v[162:163], 0, v[146:147]
	v_lshl_add_u64 v[166:167], v[136:137], 0, v[166:167]
	v_pk_mul_f32 v[126:127], v[126:127], v[164:165] op_sel_hi:[1,0]
	v_pk_mul_f32 v[124:125], v[124:125], v[164:165] op_sel_hi:[1,0]
	v_pk_mul_f32 v[122:123], v[122:123], v[164:165] op_sel_hi:[1,0]
	v_pk_mul_f32 v[120:121], v[120:121], v[164:165] op_sel_hi:[1,0]
	v_pk_mul_f32 v[118:119], v[118:119], v[164:165] op_sel_hi:[1,0]
	v_pk_mul_f32 v[116:117], v[116:117], v[164:165] op_sel_hi:[1,0]
	v_pk_mul_f32 v[114:115], v[114:115], v[164:165] op_sel_hi:[1,0]
	v_pk_mul_f32 v[112:113], v[112:113], v[164:165] op_sel_hi:[1,0]
	v_max_f32_e32 v124, 0, v124
	v_max_f32_e32 v120, 0, v120
	v_max_f32_e32 v125, 0, v125
	v_max_f32_e32 v121, 0, v121
	v_max_f32_e32 v126, 0, v126
	v_max_f32_e32 v122, 0, v122
	v_max_f32_e32 v127, 0, v127
	v_max_f32_e32 v123, 0, v123
	v_max_f32_e32 v116, 0, v116
	v_max_f32_e32 v112, 0, v112
	v_max_f32_e32 v117, 0, v117
	v_max_f32_e32 v113, 0, v113
	v_max_f32_e32 v118, 0, v118
	v_max_f32_e32 v114, 0, v114
	v_max_f32_e32 v119, 0, v119
	v_max_f32_e32 v115, 0, v115
	v_pk_mul_f32 v[124:125], v[124:125], v[124:125]
	v_pk_mul_f32 v[120:121], v[120:121], v[120:121]
	v_pk_mul_f32 v[126:127], v[126:127], v[126:127]
	v_pk_mul_f32 v[122:123], v[122:123], v[122:123]
	v_pk_mul_f32 v[116:117], v[116:117], v[116:117]
	v_pk_mul_f32 v[164:165], v[112:113], v[112:113]
	v_pk_mul_f32 v[118:119], v[118:119], v[118:119]
	v_pk_mul_f32 v[168:169], v[114:115], v[114:115]
	v_cvt_pk_bf16_f32 v112, v124, v125
	v_cvt_pk_bf16_f32 v113, v126, v127
	v_cvt_pk_bf16_f32 v114, v120, v121
	v_cvt_pk_bf16_f32 v115, v122, v123
	v_cvt_pk_bf16_f32 v116, v116, v117
	v_cvt_pk_bf16_f32 v117, v118, v119
	v_cvt_pk_bf16_f32 v118, v164, v165
	v_cvt_pk_bf16_f32 v119, v168, v169
	global_store_dwordx4 v[162:163], v[112:115], off
	global_store_dwordx4 v[162:163], v[116:119], off offset:256
	s_waitcnt vmcnt(8)
	s_nop 1
	v_add_f32_e32 v112, v174, v175
	v_add_f32_e32 v113, v176, v177
	v_lshlrev_b64 v[114:115], 13, v[160:161]
	v_add_f32_e32 v112, v112, v113
	ds_bpermute_b32 v113, v158, v112
	v_lshl_add_u64 v[114:115], s[28:29], 0, v[114:115]
	v_lshl_add_u64 v[114:115], v[114:115], 0, v[146:147]
	s_waitcnt lgkmcnt(0)
	v_add_f32_e32 v118, v112, v113
	ds_bpermute_b32 v119, v159, v118
	v_or_b32_e32 v112, 32, v148
	v_ashrrev_i32_e32 v113, 31, v112
	v_lshlrev_b64 v[116:117], 6, v[112:113]
	v_lshl_add_u64 v[116:117], v[136:137], 0, v[116:117]
	s_waitcnt lgkmcnt(0)
	v_add_f32_e32 v118, v118, v119
	v_fmamk_f32 v118, v118, 0x3a800000, v157
	v_rsq_f32_e32 v118, v118
	s_nop 0
	v_pk_mul_f32 v[110:111], v[110:111], v[118:119] op_sel_hi:[1,0]
	v_pk_mul_f32 v[108:109], v[108:109], v[118:119] op_sel_hi:[1,0]
	v_pk_mul_f32 v[106:107], v[106:107], v[118:119] op_sel_hi:[1,0]
	v_pk_mul_f32 v[104:105], v[104:105], v[118:119] op_sel_hi:[1,0]
	v_pk_mul_f32 v[102:103], v[102:103], v[118:119] op_sel_hi:[1,0]
	v_pk_mul_f32 v[100:101], v[100:101], v[118:119] op_sel_hi:[1,0]
	v_pk_mul_f32 v[98:99], v[98:99], v[118:119] op_sel_hi:[1,0]
	v_pk_mul_f32 v[96:97], v[96:97], v[118:119] op_sel_hi:[1,0]
	v_max_f32_e32 v108, 0, v108
	v_max_f32_e32 v104, 0, v104
	v_max_f32_e32 v109, 0, v109
	v_max_f32_e32 v105, 0, v105
	v_max_f32_e32 v110, 0, v110
	v_max_f32_e32 v106, 0, v106
	v_max_f32_e32 v111, 0, v111
	v_max_f32_e32 v107, 0, v107
	v_max_f32_e32 v100, 0, v100
	v_max_f32_e32 v96, 0, v96
	v_max_f32_e32 v101, 0, v101
	v_max_f32_e32 v97, 0, v97
	v_max_f32_e32 v102, 0, v102
	v_max_f32_e32 v98, 0, v98
	v_max_f32_e32 v103, 0, v103
	v_max_f32_e32 v99, 0, v99
	v_pk_mul_f32 v[108:109], v[108:109], v[108:109]
	v_pk_mul_f32 v[104:105], v[104:105], v[104:105]
	v_pk_mul_f32 v[110:111], v[110:111], v[110:111]
	v_pk_mul_f32 v[106:107], v[106:107], v[106:107]
	v_pk_mul_f32 v[100:101], v[100:101], v[100:101]
	v_pk_mul_f32 v[118:119], v[96:97], v[96:97]
	v_pk_mul_f32 v[102:103], v[102:103], v[102:103]
	v_pk_mul_f32 v[120:121], v[98:99], v[98:99]
	v_cvt_pk_bf16_f32 v96, v108, v109
	v_cvt_pk_bf16_f32 v97, v110, v111
	v_cvt_pk_bf16_f32 v98, v104, v105
	v_cvt_pk_bf16_f32 v99, v106, v107
	v_cvt_pk_bf16_f32 v100, v100, v101
	v_cvt_pk_bf16_f32 v101, v102, v103
	v_cvt_pk_bf16_f32 v102, v118, v119
	v_cvt_pk_bf16_f32 v103, v120, v121
	global_store_dwordx4 v[114:115], v[96:99], off
	global_store_dwordx4 v[114:115], v[100:103], off offset:256
	s_waitcnt vmcnt(9)
; __device__ __forceinline__ unsigned cvt_pk_bf16(float lo, float hi) { const f32x2c_t v = {lo, hi}; const bf16x2c_t b = __builtin_convertvector(v, bf16x2c_t); return __builtin_bit_cast(unsigned, b); }
;     __device__ __forceinline__ void operator()(const f32x4 (&acc)[2][2][4][2], const Unit& u, int wr, int wc, int fr, int fq) const {
;     ...
;             for (int m = 0; m < 4; ++m) { const size_t r = (size_t)(row0 + ai * HALF + m * 16);
;                 const f32x4 pq = *(const f32x4*)(ssq + r * 16 + 4 * fq);
;                 float ss = (pq[0] + pq[1]) + (pq[2] + pq[3]); ss += __shfl_xor(ss, 16); ss += __shfl_xor(ss, 32);
;                 const float rs = __builtin_amdgcn_rsqf(ss * (1.f / DM) + RMS_EPS);
; #pragma unroll
;                 for (int bj = 0; bj < 2; ++bj) { f32x4 v0 = acc[ai][bj][m][0] * rs, v1 = acc[ai][bj][m][1] * rs;
; #pragma unroll
;                     for (int e = 0; e < 4; ++e) { const float a = fmaxf(v0[e], 0.f), b = fmaxf(v1[e], 0.f); v0[e] = a * a; v1[e] = b * b; }
;                     u32x4 w; w.x = cvt_pk_bf16(v0[0], v0[1]); w.y = cvt_pk_bf16(v0[2], v0[3]); w.z = cvt_pk_bf16(v1[0], v1[1]); w.w = cvt_pk_bf16(v1[2], v1[3]);
;                     *(u32x4*)(O + r * DFF + col0 + bj * HALF) = w; } }
	s_nop 1
	v_add_f32_e32 v96, v178, v179
	v_add_f32_e32 v97, v180, v181
	v_lshlrev_b64 v[98:99], 13, v[112:113]
	v_add_f32_e32 v96, v96, v97
	ds_bpermute_b32 v97, v158, v96
	v_lshl_add_u64 v[98:99], s[28:29], 0, v[98:99]
	v_lshl_add_u64 v[98:99], v[98:99], 0, v[146:147]
	s_waitcnt lgkmcnt(0)
	v_add_f32_e32 v102, v96, v97
	ds_bpermute_b32 v103, v159, v102
	v_or_b32_e32 v96, 48, v148
	v_ashrrev_i32_e32 v97, 31, v96
	v_lshlrev_b64 v[100:101], 6, v[96:97]
	v_lshl_add_u64 v[100:101], v[136:137], 0, v[100:101]
	s_waitcnt lgkmcnt(0)
	v_add_f32_e32 v102, v102, v103
	v_fmamk_f32 v102, v102, 0x3a800000, v157
	v_rsq_f32_e32 v102, v102
	s_nop 0
	v_pk_mul_f32 v[94:95], v[94:95], v[102:103] op_sel_hi:[1,0]
	v_pk_mul_f32 v[92:93], v[92:93], v[102:103] op_sel_hi:[1,0]
	v_pk_mul_f32 v[90:91], v[90:91], v[102:103] op_sel_hi:[1,0]
	v_pk_mul_f32 v[88:89], v[88:89], v[102:103] op_sel_hi:[1,0]
	v_pk_mul_f32 v[86:87], v[86:87], v[102:103] op_sel_hi:[1,0]
	v_pk_mul_f32 v[84:85], v[84:85], v[102:103] op_sel_hi:[1,0]
	v_pk_mul_f32 v[82:83], v[82:83], v[102:103] op_sel_hi:[1,0]
	v_pk_mul_f32 v[80:81], v[80:81], v[102:103] op_sel_hi:[1,0]
	v_max_f32_e32 v92, 0, v92
	v_max_f32_e32 v88, 0, v88
	v_max_f32_e32 v93, 0, v93
	v_max_f32_e32 v89, 0, v89
	v_max_f32_e32 v94, 0, v94
	v_max_f32_e32 v90, 0, v90
	v_max_f32_e32 v95, 0, v95
	v_max_f32_e32 v91, 0, v91
	v_max_f32_e32 v84, 0, v84
	v_max_f32_e32 v80, 0, v80
	v_max_f32_e32 v85, 0, v85
	v_max_f32_e32 v81, 0, v81
	v_max_f32_e32 v86, 0, v86
	v_max_f32_e32 v82, 0, v82
	v_max_f32_e32 v87, 0, v87
	v_max_f32_e32 v83, 0, v83
	v_pk_mul_f32 v[92:93], v[92:93], v[92:93]
	v_pk_mul_f32 v[88:89], v[88:89], v[88:89]
	v_pk_mul_f32 v[94:95], v[94:95], v[94:95]
	v_pk_mul_f32 v[90:91], v[90:91], v[90:91]
	v_pk_mul_f32 v[84:85], v[84:85], v[84:85]
	v_pk_mul_f32 v[102:103], v[80:81], v[80:81]
	v_pk_mul_f32 v[86:87], v[86:87], v[86:87]
	v_pk_mul_f32 v[104:105], v[82:83], v[82:83]
	v_cvt_pk_bf16_f32 v80, v92, v93
	v_cvt_pk_bf16_f32 v81, v94, v95
	v_cvt_pk_bf16_f32 v82, v88, v89
	v_cvt_pk_bf16_f32 v83, v90, v91
	v_cvt_pk_bf16_f32 v84, v84, v85
	v_cvt_pk_bf16_f32 v85, v86, v87
	v_cvt_pk_bf16_f32 v86, v102, v103
	v_cvt_pk_bf16_f32 v87, v104, v105
	global_store_dwordx4 v[98:99], v[80:83], off
	global_store_dwordx4 v[98:99], v[84:87], off offset:256
	s_waitcnt vmcnt(10)
	s_nop 1
	v_add_f32_e32 v80, v182, v183
	v_add_f32_e32 v81, v184, v185
	v_lshlrev_b64 v[82:83], 13, v[96:97]
	v_add_f32_e32 v80, v80, v81
	ds_bpermute_b32 v81, v158, v80
	v_lshl_add_u64 v[82:83], s[28:29], 0, v[82:83]
	v_lshl_add_u64 v[82:83], v[82:83], 0, v[146:147]
	s_waitcnt lgkmcnt(0)
	v_add_f32_e32 v86, v80, v81
	ds_bpermute_b32 v87, v159, v86
	v_add_u32_e32 v80, 0x80, v148
	v_ashrrev_i32_e32 v81, 31, v80
	v_lshlrev_b64 v[84:85], 6, v[80:81]
	v_lshl_add_u64 v[84:85], v[136:137], 0, v[84:85]
	s_waitcnt lgkmcnt(0)
	v_add_f32_e32 v86, v86, v87
	v_fmamk_f32 v86, v86, 0x3a800000, v157
	v_rsq_f32_e32 v86, v86
	s_nop 0
	v_pk_mul_f32 v[78:79], v[78:79], v[86:87] op_sel_hi:[1,0]
	v_pk_mul_f32 v[76:77], v[76:77], v[86:87] op_sel_hi:[1,0]
	v_pk_mul_f32 v[74:75], v[74:75], v[86:87] op_sel_hi:[1,0]
	v_pk_mul_f32 v[72:73], v[72:73], v[86:87] op_sel_hi:[1,0]
	v_pk_mul_f32 v[70:71], v[70:71], v[86:87] op_sel_hi:[1,0]
	v_pk_mul_f32 v[68:69], v[68:69], v[86:87] op_sel_hi:[1,0]
	v_pk_mul_f32 v[66:67], v[66:67], v[86:87] op_sel_hi:[1,0]
	v_pk_mul_f32 v[64:65], v[64:65], v[86:87] op_sel_hi:[1,0]
	v_max_f32_e32 v76, 0, v76
	v_max_f32_e32 v72, 0, v72
	v_max_f32_e32 v77, 0, v77
	v_max_f32_e32 v73, 0, v73
	v_max_f32_e32 v78, 0, v78
	v_max_f32_e32 v74, 0, v74
	v_max_f32_e32 v79, 0, v79
	v_max_f32_e32 v75, 0, v75
	v_max_f32_e32 v68, 0, v68
	v_max_f32_e32 v64, 0, v64
	v_max_f32_e32 v69, 0, v69
	v_max_f32_e32 v65, 0, v65
	v_max_f32_e32 v70, 0, v70
	v_max_f32_e32 v66, 0, v66
	v_max_f32_e32 v71, 0, v71
	v_max_f32_e32 v67, 0, v67
	v_pk_mul_f32 v[76:77], v[76:77], v[76:77]
	v_pk_mul_f32 v[72:73], v[72:73], v[72:73]
	v_pk_mul_f32 v[78:79], v[78:79], v[78:79]
	v_pk_mul_f32 v[74:75], v[74:75], v[74:75]
	v_pk_mul_f32 v[68:69], v[68:69], v[68:69]
	v_pk_mul_f32 v[86:87], v[64:65], v[64:65]
	v_pk_mul_f32 v[70:71], v[70:71], v[70:71]
	v_pk_mul_f32 v[88:89], v[66:67], v[66:67]
	v_cvt_pk_bf16_f32 v64, v76, v77
	v_cvt_pk_bf16_f32 v65, v78, v79
	v_cvt_pk_bf16_f32 v66, v72, v73
	v_cvt_pk_bf16_f32 v67, v74, v75
	v_cvt_pk_bf16_f32 v68, v68, v69
	v_cvt_pk_bf16_f32 v69, v70, v71
	v_cvt_pk_bf16_f32 v70, v86, v87
	v_cvt_pk_bf16_f32 v71, v88, v89
	global_store_dwordx4 v[82:83], v[64:67], off
	global_store_dwordx4 v[82:83], v[68:71], off offset:256
	s_waitcnt vmcnt(11)
	s_nop 1
	v_add_f32_e32 v64, v186, v187
	v_add_f32_e32 v65, v188, v189
	v_lshlrev_b64 v[66:67], 13, v[80:81]
	v_add_f32_e32 v64, v64, v65
	ds_bpermute_b32 v65, v158, v64
	v_lshl_add_u64 v[66:67], s[28:29], 0, v[66:67]
	v_lshl_add_u64 v[66:67], v[66:67], 0, v[146:147]
	s_waitcnt lgkmcnt(0)
	v_add_f32_e32 v70, v64, v65
	ds_bpermute_b32 v71, v159, v70
	v_add_u32_e32 v64, 0x90, v148
	v_ashrrev_i32_e32 v65, 31, v64
	v_lshlrev_b64 v[68:69], 6, v[64:65]
	v_lshl_add_u64 v[68:69], v[136:137], 0, v[68:69]
	s_waitcnt lgkmcnt(0)
; __device__ __forceinline__ unsigned cvt_pk_bf16(float lo, float hi) { const f32x2c_t v = {lo, hi}; const bf16x2c_t b = __builtin_convertvector(v, bf16x2c_t); return __builtin_bit_cast(unsigned, b); }
;     __device__ __forceinline__ void operator()(const f32x4 (&acc)[2][2][4][2], const Unit& u, int wr, int wc, int fr, int fq) const {
;     ...
;             for (int m = 0; m < 4; ++m) { const size_t r = (size_t)(row0 + ai * HALF + m * 16);
;                 const f32x4 pq = *(const f32x4*)(ssq + r * 16 + 4 * fq);
;                 float ss = (pq[0] + pq[1]) + (pq[2] + pq[3]); ss += __shfl_xor(ss, 16); ss += __shfl_xor(ss, 32);
;                 const float rs = __builtin_amdgcn_rsqf(ss * (1.f / DM) + RMS_EPS);
; #pragma unroll
;                 for (int bj = 0; bj < 2; ++bj) { f32x4 v0 = acc[ai][bj][m][0] * rs, v1 = acc[ai][bj][m][1] * rs;
; #pragma unroll
;                     for (int e = 0; e < 4; ++e) { const float a = fmaxf(v0[e], 0.f), b = fmaxf(v1[e], 0.f); v0[e] = a * a; v1[e] = b * b; }
;                     u32x4 w; w.x = cvt_pk_bf16(v0[0], v0[1]); w.y = cvt_pk_bf16(v0[2], v0[3]); w.z = cvt_pk_bf16(v1[0], v1[1]); w.w = cvt_pk_bf16(v1[2], v1[3]);
;                     *(u32x4*)(O + r * DFF + col0 + bj * HALF) = w; } }
	v_add_f32_e32 v70, v70, v71
	v_fmamk_f32 v70, v70, 0x3a800000, v157
	v_rsq_f32_e32 v70, v70
	s_nop 0
	v_pk_mul_f32 v[62:63], v[62:63], v[70:71] op_sel_hi:[1,0]
	v_pk_mul_f32 v[60:61], v[60:61], v[70:71] op_sel_hi:[1,0]
	v_pk_mul_f32 v[58:59], v[58:59], v[70:71] op_sel_hi:[1,0]
	v_pk_mul_f32 v[56:57], v[56:57], v[70:71] op_sel_hi:[1,0]
	v_pk_mul_f32 v[54:55], v[54:55], v[70:71] op_sel_hi:[1,0]
	v_pk_mul_f32 v[52:53], v[52:53], v[70:71] op_sel_hi:[1,0]
	v_pk_mul_f32 v[50:51], v[50:51], v[70:71] op_sel_hi:[1,0]
	v_pk_mul_f32 v[48:49], v[48:49], v[70:71] op_sel_hi:[1,0]
	v_max_f32_e32 v60, 0, v60
	v_max_f32_e32 v56, 0, v56
	v_max_f32_e32 v61, 0, v61
	v_max_f32_e32 v57, 0, v57
	v_max_f32_e32 v62, 0, v62
	v_max_f32_e32 v58, 0, v58
	v_max_f32_e32 v63, 0, v63
	v_max_f32_e32 v59, 0, v59
	v_max_f32_e32 v52, 0, v52
	v_max_f32_e32 v48, 0, v48
	v_max_f32_e32 v53, 0, v53
	v_max_f32_e32 v49, 0, v49
	v_max_f32_e32 v54, 0, v54
	v_max_f32_e32 v50, 0, v50
	v_max_f32_e32 v55, 0, v55
	v_max_f32_e32 v51, 0, v51
	v_pk_mul_f32 v[60:61], v[60:61], v[60:61]
	v_pk_mul_f32 v[56:57], v[56:57], v[56:57]
	v_pk_mul_f32 v[62:63], v[62:63], v[62:63]
	v_pk_mul_f32 v[58:59], v[58:59], v[58:59]
	v_pk_mul_f32 v[52:53], v[52:53], v[52:53]
	v_pk_mul_f32 v[70:71], v[48:49], v[48:49]
	v_pk_mul_f32 v[54:55], v[54:55], v[54:55]
	v_pk_mul_f32 v[72:73], v[50:51], v[50:51]
	v_cvt_pk_bf16_f32 v48, v60, v61
	v_cvt_pk_bf16_f32 v49, v62, v63
	v_cvt_pk_bf16_f32 v50, v56, v57
	v_cvt_pk_bf16_f32 v51, v58, v59
	v_cvt_pk_bf16_f32 v52, v52, v53
	v_cvt_pk_bf16_f32 v53, v54, v55
	v_cvt_pk_bf16_f32 v54, v70, v71
	v_cvt_pk_bf16_f32 v55, v72, v73
	global_store_dwordx4 v[66:67], v[48:51], off
	global_store_dwordx4 v[66:67], v[52:55], off offset:256
	s_waitcnt vmcnt(12)
	s_nop 1
	v_add_f32_e32 v48, v190, v191
	v_add_f32_e32 v49, v192, v193
	v_lshlrev_b64 v[50:51], 13, v[64:65]
	v_add_f32_e32 v48, v48, v49
	ds_bpermute_b32 v49, v158, v48
	v_lshl_add_u64 v[50:51], s[28:29], 0, v[50:51]
	v_lshl_add_u64 v[50:51], v[50:51], 0, v[146:147]
	s_waitcnt lgkmcnt(0)
	v_add_f32_e32 v54, v48, v49
	ds_bpermute_b32 v55, v159, v54
	v_add_u32_e32 v48, 0xa0, v148
	v_ashrrev_i32_e32 v49, 31, v48
	v_lshlrev_b64 v[52:53], 6, v[48:49]
	v_lshl_add_u64 v[52:53], v[136:137], 0, v[52:53]
	s_waitcnt lgkmcnt(0)
	v_add_f32_e32 v54, v54, v55
	v_fmamk_f32 v54, v54, 0x3a800000, v157
	v_rsq_f32_e32 v54, v54
	s_nop 0
	v_pk_mul_f32 v[46:47], v[46:47], v[54:55] op_sel_hi:[1,0]
	v_pk_mul_f32 v[44:45], v[44:45], v[54:55] op_sel_hi:[1,0]
	v_pk_mul_f32 v[42:43], v[42:43], v[54:55] op_sel_hi:[1,0]
	v_pk_mul_f32 v[40:41], v[40:41], v[54:55] op_sel_hi:[1,0]
	v_pk_mul_f32 v[38:39], v[38:39], v[54:55] op_sel_hi:[1,0]
	v_pk_mul_f32 v[36:37], v[36:37], v[54:55] op_sel_hi:[1,0]
	v_pk_mul_f32 v[34:35], v[34:35], v[54:55] op_sel_hi:[1,0]
	v_pk_mul_f32 v[32:33], v[32:33], v[54:55] op_sel_hi:[1,0]
	v_max_f32_e32 v44, 0, v44
	v_max_f32_e32 v40, 0, v40
	v_max_f32_e32 v45, 0, v45
	v_max_f32_e32 v41, 0, v41
	v_max_f32_e32 v46, 0, v46
	v_max_f32_e32 v42, 0, v42
	v_max_f32_e32 v47, 0, v47
	v_max_f32_e32 v43, 0, v43
	v_max_f32_e32 v36, 0, v36
	v_max_f32_e32 v32, 0, v32
	v_max_f32_e32 v37, 0, v37
	v_max_f32_e32 v33, 0, v33
	v_max_f32_e32 v38, 0, v38
	v_max_f32_e32 v34, 0, v34
	v_max_f32_e32 v39, 0, v39
	v_max_f32_e32 v35, 0, v35
	v_pk_mul_f32 v[44:45], v[44:45], v[44:45]
	v_pk_mul_f32 v[40:41], v[40:41], v[40:41]
	v_pk_mul_f32 v[46:47], v[46:47], v[46:47]
	v_pk_mul_f32 v[42:43], v[42:43], v[42:43]
	v_pk_mul_f32 v[36:37], v[36:37], v[36:37]
	v_pk_mul_f32 v[54:55], v[32:33], v[32:33]
	v_pk_mul_f32 v[38:39], v[38:39], v[38:39]
	v_pk_mul_f32 v[56:57], v[34:35], v[34:35]
	v_cvt_pk_bf16_f32 v32, v44, v45
	v_cvt_pk_bf16_f32 v33, v46, v47
	v_cvt_pk_bf16_f32 v34, v40, v41
	v_cvt_pk_bf16_f32 v35, v42, v43
	v_cvt_pk_bf16_f32 v36, v36, v37
	v_cvt_pk_bf16_f32 v37, v38, v39
	v_cvt_pk_bf16_f32 v38, v54, v55
	v_cvt_pk_bf16_f32 v39, v56, v57
	global_store_dwordx4 v[50:51], v[32:35], off
	global_store_dwordx4 v[50:51], v[36:39], off offset:256
	s_waitcnt vmcnt(13)
	s_nop 1
	v_add_f32_e32 v32, v194, v195
	v_add_f32_e32 v33, v196, v197
	v_lshlrev_b64 v[34:35], 13, v[48:49]
	v_add_f32_e32 v32, v32, v33
	ds_bpermute_b32 v33, v158, v32
	v_lshl_add_u64 v[34:35], s[28:29], 0, v[34:35]
	v_lshl_add_u64 v[34:35], v[34:35], 0, v[146:147]
	s_waitcnt lgkmcnt(0)
; __device__ __forceinline__ unsigned cvt_pk_bf16(float lo, float hi) { const f32x2c_t v = {lo, hi}; const bf16x2c_t b = __builtin_convertvector(v, bf16x2c_t); return __builtin_bit_cast(unsigned, b); }
; #define PG8_BAR __builtin_amdgcn_s_barrier()
; template <class Epi, class Sched, bool ALIGN_EPI = false, bool SP2 = false, bool FP8 = false>
; __device__ __forceinline__ void gemm_phase(PG8_LAS unsigned char* lds, const Gemm g, const Sched& S, const Epi& E) {
;     ...
;         if constexpr (ALIGN_EPI) { if (wr == 1) PG8_BAR; }
;     __device__ __forceinline__ void operator()(const f32x4 (&acc)[2][2][4][2], const Unit& u, int wr, int wc, int fr, int fq) const {
;     ...
;             for (int m = 0; m < 4; ++m) { const size_t r = (size_t)(row0 + ai * HALF + m * 16);
;                 const f32x4 pq = *(const f32x4*)(ssq + r * 16 + 4 * fq);
;                 float ss = (pq[0] + pq[1]) + (pq[2] + pq[3]); ss += __shfl_xor(ss, 16); ss += __shfl_xor(ss, 32);
;                 const float rs = __builtin_amdgcn_rsqf(ss * (1.f / DM) + RMS_EPS);
; #pragma unroll
;                 for (int bj = 0; bj < 2; ++bj) { f32x4 v0 = acc[ai][bj][m][0] * rs, v1 = acc[ai][bj][m][1] * rs;
; #pragma unroll
;                     for (int e = 0; e < 4; ++e) { const float a = fmaxf(v0[e], 0.f), b = fmaxf(v1[e], 0.f); v0[e] = a * a; v1[e] = b * b; }
;                     u32x4 w; w.x = cvt_pk_bf16(v0[0], v0[1]); w.y = cvt_pk_bf16(v0[2], v0[3]); w.z = cvt_pk_bf16(v1[0], v1[1]); w.w = cvt_pk_bf16(v1[2], v1[3]);
;                     *(u32x4*)(O + r * DFF + col0 + bj * HALF) = w; } }
	v_add_f32_e32 v38, v32, v33
	ds_bpermute_b32 v39, v159, v38
	v_add_u32_e32 v32, 0xb0, v148
	v_ashrrev_i32_e32 v33, 31, v32
	v_lshlrev_b64 v[36:37], 6, v[32:33]
	v_lshl_add_u64 v[36:37], v[136:137], 0, v[36:37]
	s_waitcnt lgkmcnt(0)
	v_add_f32_e32 v38, v38, v39
	v_fmamk_f32 v38, v38, 0x3a800000, v157
	v_rsq_f32_e32 v38, v38
	s_nop 0
	v_pk_mul_f32 v[30:31], v[30:31], v[38:39] op_sel_hi:[1,0]
	v_pk_mul_f32 v[28:29], v[28:29], v[38:39] op_sel_hi:[1,0]
	v_pk_mul_f32 v[26:27], v[26:27], v[38:39] op_sel_hi:[1,0]
	v_pk_mul_f32 v[24:25], v[24:25], v[38:39] op_sel_hi:[1,0]
	v_pk_mul_f32 v[22:23], v[22:23], v[38:39] op_sel_hi:[1,0]
	v_pk_mul_f32 v[20:21], v[20:21], v[38:39] op_sel_hi:[1,0]
	v_pk_mul_f32 v[18:19], v[18:19], v[38:39] op_sel_hi:[1,0]
	v_pk_mul_f32 v[16:17], v[16:17], v[38:39] op_sel_hi:[1,0]
	v_max_f32_e32 v28, 0, v28
	v_max_f32_e32 v24, 0, v24
	v_max_f32_e32 v29, 0, v29
	v_max_f32_e32 v25, 0, v25
	v_max_f32_e32 v30, 0, v30
	v_max_f32_e32 v26, 0, v26
	v_max_f32_e32 v31, 0, v31
	v_max_f32_e32 v27, 0, v27
	v_max_f32_e32 v20, 0, v20
	v_max_f32_e32 v16, 0, v16
	v_max_f32_e32 v21, 0, v21
	v_max_f32_e32 v17, 0, v17
	v_max_f32_e32 v22, 0, v22
	v_max_f32_e32 v18, 0, v18
	v_max_f32_e32 v23, 0, v23
	v_max_f32_e32 v19, 0, v19
	v_pk_mul_f32 v[28:29], v[28:29], v[28:29]
	v_pk_mul_f32 v[24:25], v[24:25], v[24:25]
	v_pk_mul_f32 v[30:31], v[30:31], v[30:31]
	v_pk_mul_f32 v[26:27], v[26:27], v[26:27]
	v_pk_mul_f32 v[20:21], v[20:21], v[20:21]
	v_pk_mul_f32 v[38:39], v[16:17], v[16:17]
	v_pk_mul_f32 v[22:23], v[22:23], v[22:23]
	v_pk_mul_f32 v[40:41], v[18:19], v[18:19]
	v_cvt_pk_bf16_f32 v16, v28, v29
	v_cvt_pk_bf16_f32 v17, v30, v31
	v_cvt_pk_bf16_f32 v18, v24, v25
	v_cvt_pk_bf16_f32 v19, v26, v27
	v_cvt_pk_bf16_f32 v20, v20, v21
	v_cvt_pk_bf16_f32 v21, v22, v23
	v_cvt_pk_bf16_f32 v22, v38, v39
	v_cvt_pk_bf16_f32 v23, v40, v41
	global_store_dwordx4 v[34:35], v[16:19], off
	global_store_dwordx4 v[34:35], v[20:23], off offset:256
	s_waitcnt vmcnt(14)
	s_nop 1
	v_add_f32_e32 v16, v198, v199
	v_add_f32_e32 v17, v200, v201
	v_lshlrev_b64 v[18:19], 13, v[32:33]
	v_add_f32_e32 v16, v16, v17
	ds_bpermute_b32 v17, v158, v16
	v_lshl_add_u64 v[18:19], s[28:29], 0, v[18:19]
	v_lshl_add_u64 v[18:19], v[18:19], 0, v[146:147]
	s_waitcnt lgkmcnt(0)
	v_add_f32_e32 v16, v16, v17
	ds_bpermute_b32 v17, v159, v16
	s_waitcnt lgkmcnt(0)
	v_add_f32_e32 v16, v16, v17
	v_fmamk_f32 v16, v16, 0x3a800000, v157
	v_rsq_f32_e32 v16, v16
	s_nop 0
	v_pk_mul_f32 v[14:15], v[14:15], v[16:17] op_sel_hi:[1,0]
	v_pk_mul_f32 v[12:13], v[12:13], v[16:17] op_sel_hi:[1,0]
	v_pk_mul_f32 v[10:11], v[10:11], v[16:17] op_sel_hi:[1,0]
	v_pk_mul_f32 v[8:9], v[8:9], v[16:17] op_sel_hi:[1,0]
	v_pk_mul_f32 v[6:7], v[6:7], v[16:17] op_sel_hi:[1,0]
	v_pk_mul_f32 v[4:5], v[4:5], v[16:17] op_sel_hi:[1,0]
	v_pk_mul_f32 v[2:3], v[2:3], v[16:17] op_sel_hi:[1,0]
	v_pk_mul_f32 v[0:1], v[0:1], v[16:17] op_sel_hi:[1,0]
	v_max_f32_e32 v12, 0, v12
	v_max_f32_e32 v8, 0, v8
	v_max_f32_e32 v13, 0, v13
	v_max_f32_e32 v9, 0, v9
	v_max_f32_e32 v14, 0, v14
	v_max_f32_e32 v10, 0, v10
	v_max_f32_e32 v15, 0, v15
	v_max_f32_e32 v11, 0, v11
	v_max_f32_e32 v4, 0, v4
	v_max_f32_e32 v0, 0, v0
	v_max_f32_e32 v5, 0, v5
	v_max_f32_e32 v1, 0, v1
	v_max_f32_e32 v6, 0, v6
	v_max_f32_e32 v2, 0, v2
	v_max_f32_e32 v7, 0, v7
	v_max_f32_e32 v3, 0, v3
	v_pk_mul_f32 v[12:13], v[12:13], v[12:13]
	v_pk_mul_f32 v[8:9], v[8:9], v[8:9]
	v_pk_mul_f32 v[14:15], v[14:15], v[14:15]
	v_pk_mul_f32 v[10:11], v[10:11], v[10:11]
	v_pk_mul_f32 v[4:5], v[4:5], v[4:5]
	v_pk_mul_f32 v[16:17], v[0:1], v[0:1]
	v_pk_mul_f32 v[6:7], v[6:7], v[6:7]
	v_pk_mul_f32 v[20:21], v[2:3], v[2:3]
	v_cvt_pk_bf16_f32 v0, v12, v13
	v_cvt_pk_bf16_f32 v1, v14, v15
	v_cvt_pk_bf16_f32 v2, v8, v9
	v_cvt_pk_bf16_f32 v3, v10, v11
	v_cvt_pk_bf16_f32 v4, v4, v5
	v_cvt_pk_bf16_f32 v5, v6, v7
	v_cvt_pk_bf16_f32 v6, v16, v17
	v_cvt_pk_bf16_f32 v7, v20, v21
	global_store_dwordx4 v[18:19], v[0:3], off
	global_store_dwordx4 v[18:19], v[4:7], off offset:256
	s_cbranch_vccnz .LBB0_387
	s_andn2_b64 vcc, exec, s[6:7]
	s_cbranch_vccnz .LBB0_386
	s_barrier
	s_branch .LBB0_386
